# attention PV: counted lgkmcnt waits per MFMA instead of lgkmcnt(0) per group of four
# baseline (speedup 1.0000x reference)
.LBB0_453:
	ds_read_b128 v[66:69], v209 offset:49152
	ds_read_b128 v[70:73], v209 offset:57344
	ds_read_b128 v[232:235], v214 offset:49152
	ds_read_b128 v[236:239], v214 offset:57344
	ds_read_b128 v[200:203], v213 offset:49152
	ds_read_b128 v[204:207], v213 offset:57344
	v_add_f32_e32 v164, 0, v165
	v_add_f32_e32 v164, v179, v164
	s_waitcnt lgkmcnt(5)
	v_mfma_f32_32x32x16_bf16 v[82:97], v[66:69], v[120:123], 0
	v_add_f32_e32 v164, v166, v164
	v_add_f32_e32 v164, v221, v164
	v_add_f32_e32 v164, v178, v164
	v_add_f32_e32 v164, v231, v164
	v_add_f32_e32 v164, v167, v164
	v_add_f32_e32 v164, v177, v164
	v_add_f32_e32 v164, v173, v164
	s_waitcnt lgkmcnt(4)
	v_mfma_f32_32x32x16_bf16 v[66:81], v[70:73], v[120:123], 0
	v_add_f32_e32 v164, v175, v164
	v_add_f32_e32 v164, v174, v164
	v_add_f32_e32 v164, v176, v164
	v_exp_f32_e32 v162, v162
	v_add_f32_e32 v164, v169, v164
	v_exp_f32_e32 v163, v163
	v_add_f32_e32 v164, v171, v164
	s_waitcnt lgkmcnt(3)
	v_mfma_f32_32x32x16_bf16 v[82:97], v[232:235], v[112:115], v[82:97]
	v_exp_f32_e32 v160, v160
	v_add_f32_e32 v164, v170, v164
	v_exp_f32_e32 v161, v161
	v_add_f32_e32 v164, v172, v164
	v_exp_f32_e32 v156, v156
	v_add_f32_e32 v164, v162, v164
	v_exp_f32_e32 v157, v157
	s_waitcnt lgkmcnt(2)
	v_mfma_f32_32x32x16_bf16 v[66:81], v[236:239], v[112:115], v[66:81]
	ds_read_b128 v[232:235], v212 offset:49152
	ds_read_b128 v[236:239], v212 offset:57344
	v_add_f32_e32 v164, v163, v164
	v_exp_f32_e32 v152, v152
	v_add_f32_e32 v164, v160, v164
	v_exp_f32_e32 v153, v153
	v_add_f32_e32 v164, v161, v164
	v_exp_f32_e32 v150, v150
	s_waitcnt lgkmcnt(3)
	v_mfma_f32_32x32x16_bf16 v[82:97], v[200:203], v[128:131], v[82:97]
	v_add_f32_e32 v164, v156, v164
	v_exp_f32_e32 v151, v151
	v_add_f32_e32 v164, v157, v164
	v_exp_f32_e32 v158, v158
	v_add_f32_e32 v164, v152, v164
	v_exp_f32_e32 v159, v159
	v_add_f32_e32 v164, v153, v164
	s_waitcnt lgkmcnt(2)
	v_mfma_f32_32x32x16_bf16 v[66:81], v[204:207], v[128:131], v[66:81]
	ds_read_b128 v[200:203], v211 offset:49152
	ds_read_b128 v[204:207], v211 offset:57344
	v_exp_f32_e32 v154, v154
	v_add_f32_e32 v164, v150, v164
	v_exp_f32_e32 v155, v155
	v_add_f32_e32 v164, v151, v164
	v_exp_f32_e32 v148, v148
	v_add_f32_e32 v164, v158, v164
	s_waitcnt lgkmcnt(3)
	v_mfma_f32_32x32x16_bf16 v[82:97], v[232:235], v[124:127], v[82:97]
	v_exp_f32_e32 v149, v149
	v_add_f32_e32 v164, v159, v164
	v_add_f32_e32 v164, v154, v164
	v_add_f32_e32 v164, v155, v164
	v_add_f32_e32 v164, v148, v164
	v_add_f32_e32 v218, v149, v164
	v_mov_b32_e32 v219, v218
	s_waitcnt lgkmcnt(2)
	v_mfma_f32_32x32x16_bf16 v[66:81], v[236:239], v[124:127], v[66:81]
	ds_read_b128 v[232:235], v210 offset:49152
	ds_read_b128 v[236:239], v210 offset:57344
	v_permlane32_swap_b32_e32 v218, v219
	s_waitcnt lgkmcnt(3)
	v_mfma_f32_32x32x16_bf16 v[82:97], v[200:203], v[116:119], v[82:97]
	s_waitcnt lgkmcnt(2)
	v_mfma_f32_32x32x16_bf16 v[66:81], v[204:207], v[116:119], v[66:81]
	ds_read_b128 v[200:203], v216 offset:49152
	ds_read_b128 v[204:207], v216 offset:57344
	s_waitcnt lgkmcnt(3)
	v_mfma_f32_32x32x16_bf16 v[82:97], v[232:235], v[108:111], v[82:97]
	s_waitcnt lgkmcnt(2)
	v_mfma_f32_32x32x16_bf16 v[66:81], v[236:239], v[108:111], v[66:81]
	ds_read_b128 v[232:235], v215 offset:49152
	ds_read_b128 v[236:239], v215 offset:57344
	s_waitcnt lgkmcnt(3)
	v_mfma_f32_32x32x16_bf16 v[82:97], v[200:203], v[104:107], v[82:97]
	s_waitcnt lgkmcnt(2)
	v_mfma_f32_32x32x16_bf16 v[66:81], v[204:207], v[104:107], v[66:81]
	v_cvt_pk_bf16_f32 v164, v165, v179
	v_cvt_pk_bf16_f32 v165, v166, v221
	v_cvt_pk_bf16_f32 v166, v178, v231
	v_cvt_pk_bf16_f32 v167, v167, v177
	v_cvt_pk_bf16_f32 v220, v173, v175
	v_cvt_pk_bf16_f32 v221, v174, v176
	s_waitcnt lgkmcnt(1)
	v_mfma_f32_32x32x16_bf16 v[82:97], v[232:235], v[100:103], v[82:97]
	v_cvt_pk_bf16_f32 v222, v169, v171
	v_permlane32_swap_b32_e32 v164, v166
	v_cvt_pk_bf16_f32 v223, v170, v172
	v_permlane32_swap_b32_e32 v220, v222
	v_cvt_pk_bf16_f32 v170, v162, v163
	s_waitcnt lgkmcnt(0)
	v_mfma_f32_32x32x16_bf16 v[66:81], v[236:239], v[100:103], v[66:81]
	ds_read_b64_tr_b16 v[232:233], v192 offset:0
	ds_read_b64_tr_b16 v[234:235], v192 offset:0x800
	ds_read_b64_tr_b16 v[236:237], v192 offset:0x1000
	ds_read_b64_tr_b16 v[238:239], v192 offset:0x1800
	ds_read_b64_tr_b16 v[240:241], v192 offset:0x2000
	ds_read_b64_tr_b16 v[242:243], v192 offset:0x2800
	ds_read_b64_tr_b16 v[244:245], v192 offset:0x3000
	ds_read_b64_tr_b16 v[246:247], v192 offset:0x3800
	v_cvt_pk_bf16_f32 v171, v160, v161
	v_cvt_pk_bf16_f32 v172, v156, v157
	v_cvt_pk_bf16_f32 v173, v152, v153
	v_cvt_pk_bf16_f32 v174, v150, v151
	v_cvt_pk_bf16_f32 v175, v158, v159
	v_cvt_pk_bf16_f32 v176, v154, v155
	v_cvt_pk_bf16_f32 v177, v148, v149
	v_permlane32_swap_b32_e32 v165, v167
	v_permlane32_swap_b32_e32 v221, v223
	v_permlane32_swap_b32_e32 v170, v172
	v_permlane32_swap_b32_e32 v171, v173
	v_permlane32_swap_b32_e32 v174, v176
	v_permlane32_swap_b32_e32 v175, v177
	v_add_co_u32_e32 v148, vcc, s1, v180
	s_nop 1
	v_addc_co_u32_e32 v149, vcc, -1, v181, vcc
	v_add_co_u32_e32 v152, vcc, s28, v180
	s_nop 1
	v_addc_co_u32_e32 v153, vcc, -1, v181, vcc
	v_add_co_u32_e32 v156, vcc, s19, v180
	global_load_dwordx4 v[148:151], v[148:149], off
	s_nop 0
	global_load_dwordx4 v[152:155], v[152:153], off
	v_addc_co_u32_e32 v157, vcc, -1, v181, vcc
	v_add_co_u32_e32 v160, vcc, s27, v180
	s_nop 1
	v_addc_co_u32_e32 v161, vcc, -1, v181, vcc
	global_load_dwordx4 v[156:159], v[156:157], off
	s_nop 0
	global_load_dwordx4 v[160:163], v[160:161], off
	s_nop 0
	s_waitcnt lgkmcnt(6)
	v_mfma_f32_32x32x16_bf16 v[2:17], v[164:167], v[232:235], v[2:17]
	ds_read_b64_tr_b16 v[232:233], v192 offset:0x200
	ds_read_b64_tr_b16 v[234:235], v192 offset:0xa00
	s_waitcnt lgkmcnt(6)
	v_mfma_f32_32x32x16_bf16 v[2:17], v[220:223], v[236:239], v[2:17]
	ds_read_b64_tr_b16 v[236:237], v192 offset:0x1200
	ds_read_b64_tr_b16 v[238:239], v192 offset:0x1a00
	s_waitcnt lgkmcnt(6)
	v_mfma_f32_32x32x16_bf16 v[2:17], v[170:173], v[240:243], v[2:17]
	ds_read_b64_tr_b16 v[240:241], v192 offset:0x2200
	ds_read_b64_tr_b16 v[242:243], v192 offset:0x2a00
	s_waitcnt lgkmcnt(6)
	v_mfma_f32_32x32x16_bf16 v[2:17], v[174:177], v[244:247], v[2:17]
	ds_read_b64_tr_b16 v[244:245], v192 offset:0x3200
	ds_read_b64_tr_b16 v[246:247], v192 offset:0x3a00
	s_waitcnt lgkmcnt(6)
	v_mfma_f32_32x32x16_bf16 v[50:65], v[164:167], v[232:235], v[50:65]
	ds_read_b64_tr_b16 v[232:233], v192 offset:0x400
	ds_read_b64_tr_b16 v[234:235], v192 offset:0xc00
	s_waitcnt lgkmcnt(6)
	v_mfma_f32_32x32x16_bf16 v[50:65], v[220:223], v[236:239], v[50:65]
	ds_read_b64_tr_b16 v[236:237], v192 offset:0x1400
	ds_read_b64_tr_b16 v[238:239], v192 offset:0x1c00
	s_waitcnt lgkmcnt(6)
	v_mfma_f32_32x32x16_bf16 v[50:65], v[170:173], v[240:243], v[50:65]
	ds_read_b64_tr_b16 v[240:241], v192 offset:0x2400
	ds_read_b64_tr_b16 v[242:243], v192 offset:0x2c00
	s_waitcnt lgkmcnt(6)
	v_mfma_f32_32x32x16_bf16 v[50:65], v[174:177], v[244:247], v[50:65]
	ds_read_b64_tr_b16 v[244:245], v192 offset:0x3400
	ds_read_b64_tr_b16 v[246:247], v192 offset:0x3c00
	s_waitcnt lgkmcnt(6)
	v_mfma_f32_32x32x16_bf16 v[34:49], v[164:167], v[232:235], v[34:49]
	ds_read_b64_tr_b16 v[232:233], v192 offset:0x600
	ds_read_b64_tr_b16 v[234:235], v192 offset:0xe00
	s_waitcnt lgkmcnt(6)
	v_mfma_f32_32x32x16_bf16 v[34:49], v[220:223], v[236:239], v[34:49]
	ds_read_b64_tr_b16 v[236:237], v192 offset:0x1600
	ds_read_b64_tr_b16 v[238:239], v192 offset:0x1e00
	s_waitcnt lgkmcnt(6)
	v_mfma_f32_32x32x16_bf16 v[34:49], v[170:173], v[240:243], v[34:49]
	ds_read_b64_tr_b16 v[240:241], v192 offset:0x2600
	ds_read_b64_tr_b16 v[242:243], v192 offset:0x2e00
	s_waitcnt lgkmcnt(6)
	v_mfma_f32_32x32x16_bf16 v[34:49], v[174:177], v[244:247], v[34:49]
	ds_read_b64_tr_b16 v[244:245], v192 offset:0x3600
	ds_read_b64_tr_b16 v[246:247], v192 offset:0x3e00
	s_waitcnt lgkmcnt(6)
	v_mfma_f32_32x32x16_bf16 v[18:33], v[164:167], v[232:235], v[18:33]
	v_max_f32_e32 v164, v83, v83
	v_max_f32_e32 v165, v82, v82
	v_max_f32_e32 v164, v165, v164
	v_max3_f32 v164, v164, v84, v85
	v_max3_f32 v164, v164, v86, v87
	v_max3_f32 v164, v164, v88, v89
	v_max3_f32 v164, v164, v90, v91
	v_max3_f32 v164, v164, v92, v93
	v_max3_f32 v164, v164, v94, v95
	s_waitcnt lgkmcnt(4)
	v_mfma_f32_32x32x16_bf16 v[18:33], v[220:223], v[236:239], v[18:33]
	v_max3_f32 v164, v164, v96, v97
	v_max3_f32 v164, v164, v66, v67
	v_max3_f32 v164, v164, v68, v69
	v_max3_f32 v164, v164, v70, v71
	v_max3_f32 v164, v164, v72, v73
	v_max3_f32 v164, v164, v74, v75
	v_max3_f32 v164, v164, v76, v77
	v_max3_f32 v164, v164, v78, v79
	s_waitcnt lgkmcnt(2)
	v_mfma_f32_32x32x16_bf16 v[18:33], v[170:173], v[240:243], v[18:33]
	v_max3_f32 v164, v164, v80, v81
	v_mov_b32_e32 v165, v164
	s_nop 1
	v_permlane32_swap_b32_e32 v164, v165
	v_max_f32_e32 v165, v165, v165
	v_max_f32_e32 v164, v164, v164
	v_max_f32_e32 v164, v164, v165
	v_sub_f32_e32 v165, v164, v168
	v_cmp_ge_f32_e32 vcc, s0, v165
	v_max_f32_e32 v165, v168, v168
	v_max_f32_e32 v164, v165, v164
	s_waitcnt lgkmcnt(0)
	v_mfma_f32_32x32x16_bf16 v[18:33], v[174:177], v[244:247], v[18:33]
	v_sub_f32_e32 v165, v168, v164
	v_mul_f32_e32 v165, 0x3e0293ee, v165
	v_exp_f32_e32 v165, v165
	s_cmp_eq_u64 vcc, exec
	s_cselect_b64 s[42:43], -1, 0
	s_barrier
	s_waitcnt vmcnt(4)
	v_cndmask_b32_e64 v220, v165, 1.0, s[42:43]
	v_cmp_gt_f32_e32 vcc, 1.0, v220
	s_waitcnt vmcnt(7)
	ds_write_b128 v195, v[132:135]
	s_waitcnt vmcnt(6)
	ds_write_b128 v208, v[140:143]
	s_waitcnt vmcnt(5)
	ds_write_b128 v193, v[136:139] offset:32768
	s_waitcnt vmcnt(4)
	ds_write_b128 v194, v[144:147] offset:32768
	s_cbranch_vccz .LBB0_457
	s_and_saveexec_b64 s[4:5], s[40:41]
	ds_write_b32 v189, v220 offset:128
	s_or_b64 exec, exec, s[4:5]
	s_waitcnt lgkmcnt(0)
	v_add_u32_e32 v165, v188, v98
	ds_read_b128 v[170:173], v165 offset:224
	ds_read_b128 v[174:177], v165 offset:192
	ds_read_b128 v[232:235], v165 offset:160
	ds_read_b128 v[236:239], v165 offset:128
	s_waitcnt lgkmcnt(3)
	v_pk_mul_f32 v[14:15], v[14:15], v[170:171]
	s_waitcnt lgkmcnt(2)
	v_pk_mul_f32 v[10:11], v[10:11], v[174:175]
	s_waitcnt lgkmcnt(1)
	v_pk_mul_f32 v[6:7], v[6:7], v[232:233]
	v_pk_mul_f32 v[16:17], v[16:17], v[172:173]
	v_pk_mul_f32 v[12:13], v[12:13], v[176:177]
	v_pk_mul_f32 v[8:9], v[8:9], v[234:235]
	s_waitcnt lgkmcnt(0)
	v_pk_mul_f32 v[4:5], v[4:5], v[238:239]
	v_pk_mul_f32 v[2:3], v[2:3], v[236:237]
	v_pk_mul_f32 v[62:63], v[62:63], v[170:171]
	v_pk_mul_f32 v[58:59], v[58:59], v[174:175]
	v_pk_mul_f32 v[54:55], v[54:55], v[232:233]
	v_pk_mul_f32 v[64:65], v[64:65], v[172:173]
	v_pk_mul_f32 v[60:61], v[60:61], v[176:177]
	v_pk_mul_f32 v[56:57], v[56:57], v[234:235]
	v_pk_mul_f32 v[52:53], v[52:53], v[238:239]
	v_pk_mul_f32 v[50:51], v[50:51], v[236:237]
	v_pk_mul_f32 v[46:47], v[46:47], v[170:171]
	v_pk_mul_f32 v[42:43], v[42:43], v[174:175]
	v_pk_mul_f32 v[38:39], v[38:39], v[232:233]
	v_pk_mul_f32 v[48:49], v[48:49], v[172:173]
	v_pk_mul_f32 v[44:45], v[44:45], v[176:177]
	v_pk_mul_f32 v[40:41], v[40:41], v[234:235]
	v_pk_mul_f32 v[36:37], v[36:37], v[238:239]
	v_pk_mul_f32 v[34:35], v[34:35], v[236:237]
	v_pk_mul_f32 v[30:31], v[30:31], v[170:171]
	v_pk_mul_f32 v[26:27], v[26:27], v[174:175]
	v_pk_mul_f32 v[22:23], v[22:23], v[232:233]
	v_pk_mul_f32 v[32:33], v[32:33], v[172:173]
	v_pk_mul_f32 v[28:29], v[28:29], v[176:177]
	v_pk_mul_f32 v[24:25], v[24:25], v[234:235]
	v_pk_mul_f32 v[20:21], v[20:21], v[238:239]
	v_pk_mul_f32 v[18:19], v[18:19], v[236:237]

.LBB0_459:
	ds_read_b64_tr_b16 v[196:197], v191 offset:0
	ds_read_b64_tr_b16 v[198:199], v191 offset:0x800
	ds_read_b64_tr_b16 v[232:233], v191 offset:0x1000
	ds_read_b64_tr_b16 v[234:235], v191 offset:0x1800
	ds_read_b64_tr_b16 v[236:237], v191 offset:0x2000
	ds_read_b64_tr_b16 v[238:239], v191 offset:0x2800
	ds_read_b64_tr_b16 v[240:241], v191 offset:0x3000
	ds_read_b64_tr_b16 v[242:243], v191 offset:0x3800
	s_nop 0
	s_waitcnt lgkmcnt(6)
	v_mfma_f32_32x32x16_bf16 v[2:17], v[164:167], v[196:199], v[2:17]
	ds_read_b64_tr_b16 v[196:197], v191 offset:0x200
	ds_read_b64_tr_b16 v[198:199], v191 offset:0xa00
	s_waitcnt lgkmcnt(6)
	v_mfma_f32_32x32x16_bf16 v[2:17], v[168:171], v[232:235], v[2:17]
	ds_read_b64_tr_b16 v[232:233], v191 offset:0x1200
	ds_read_b64_tr_b16 v[234:235], v191 offset:0x1a00
	s_waitcnt lgkmcnt(6)
	v_mfma_f32_32x32x16_bf16 v[2:17], v[172:175], v[236:239], v[2:17]
	ds_read_b64_tr_b16 v[236:237], v191 offset:0x2200
	ds_read_b64_tr_b16 v[238:239], v191 offset:0x2a00
	s_waitcnt lgkmcnt(6)
	v_mfma_f32_32x32x16_bf16 v[2:17], v[176:179], v[240:243], v[2:17]
	ds_read_b64_tr_b16 v[240:241], v191 offset:0x3200
	ds_read_b64_tr_b16 v[242:243], v191 offset:0x3a00
	s_waitcnt lgkmcnt(6)
	v_mfma_f32_32x32x16_bf16 v[50:65], v[164:167], v[196:199], v[50:65]
	ds_read_b64_tr_b16 v[196:197], v191 offset:0x400
	ds_read_b64_tr_b16 v[198:199], v191 offset:0xc00
	s_waitcnt lgkmcnt(6)
	v_mfma_f32_32x32x16_bf16 v[50:65], v[168:171], v[232:235], v[50:65]
	ds_read_b64_tr_b16 v[232:233], v191 offset:0x1400
	ds_read_b64_tr_b16 v[234:235], v191 offset:0x1c00
	s_waitcnt lgkmcnt(6)
	v_mfma_f32_32x32x16_bf16 v[50:65], v[172:175], v[236:239], v[50:65]
	ds_read_b64_tr_b16 v[236:237], v191 offset:0x2400
	ds_read_b64_tr_b16 v[238:239], v191 offset:0x2c00
	s_waitcnt lgkmcnt(6)
	v_mfma_f32_32x32x16_bf16 v[50:65], v[176:179], v[240:243], v[50:65]
	ds_read_b64_tr_b16 v[240:241], v191 offset:0x3400
	ds_read_b64_tr_b16 v[242:243], v191 offset:0x3c00
	s_waitcnt lgkmcnt(6)
	v_mfma_f32_32x32x16_bf16 v[34:49], v[164:167], v[196:199], v[34:49]
	ds_read_b64_tr_b16 v[196:197], v191 offset:0x600
	ds_read_b64_tr_b16 v[198:199], v191 offset:0xe00
	s_waitcnt lgkmcnt(6)
	v_mfma_f32_32x32x16_bf16 v[34:49], v[168:171], v[232:235], v[34:49]
	ds_read_b64_tr_b16 v[232:233], v191 offset:0x1600
	ds_read_b64_tr_b16 v[234:235], v191 offset:0x1e00
	s_waitcnt lgkmcnt(6)
	v_mfma_f32_32x32x16_bf16 v[34:49], v[172:175], v[236:239], v[34:49]
	ds_read_b64_tr_b16 v[236:237], v191 offset:0x2600
	ds_read_b64_tr_b16 v[238:239], v191 offset:0x2e00
	s_waitcnt lgkmcnt(6)
	v_mfma_f32_32x32x16_bf16 v[34:49], v[176:179], v[240:243], v[34:49]
	ds_read_b64_tr_b16 v[240:241], v191 offset:0x3600
	ds_read_b64_tr_b16 v[242:243], v191 offset:0x3e00
	s_waitcnt lgkmcnt(6)
	v_mfma_f32_32x32x16_bf16 v[18:33], v[164:167], v[196:199], v[18:33]
	v_max_f32_e32 v164, v83, v83
	v_max_f32_e32 v165, v82, v82
	v_max_f32_e32 v164, v165, v164
	v_max3_f32 v164, v164, v84, v85
	v_max3_f32 v164, v164, v86, v87
	v_max3_f32 v164, v164, v88, v89
	v_max3_f32 v164, v164, v90, v91
	v_max3_f32 v164, v164, v92, v93
	v_max3_f32 v164, v164, v94, v95
	s_waitcnt lgkmcnt(4)
	v_mfma_f32_32x32x16_bf16 v[18:33], v[168:171], v[232:235], v[18:33]
	v_max3_f32 v164, v164, v96, v97
	v_max3_f32 v164, v164, v66, v67
	v_max3_f32 v164, v164, v68, v69
	v_max3_f32 v164, v164, v70, v71
	v_max3_f32 v164, v164, v72, v73
	v_max3_f32 v164, v164, v74, v75
	v_max3_f32 v164, v164, v76, v77
	v_max3_f32 v164, v164, v78, v79
	s_waitcnt lgkmcnt(2)
	v_mfma_f32_32x32x16_bf16 v[18:33], v[172:175], v[236:239], v[18:33]
	v_max3_f32 v164, v164, v80, v81
	v_mov_b32_e32 v165, v164
	s_nop 1
	v_permlane32_swap_b32_e32 v164, v165
	v_max_f32_e32 v165, v165, v165
	v_max_f32_e32 v164, v164, v164
	v_max_f32_e32 v164, v164, v165
	v_sub_f32_e32 v165, v164, v221
	v_cmp_ge_f32_e32 vcc, s0, v165
	v_max_f32_e32 v165, v221, v221
	v_max_f32_e32 v165, v165, v164
	s_waitcnt lgkmcnt(0)
	v_mfma_f32_32x32x16_bf16 v[18:33], v[176:179], v[240:243], v[18:33]
	v_sub_f32_e32 v164, v221, v165
	v_mul_f32_e32 v164, 0x3e0293ee, v164
	v_exp_f32_e32 v164, v164
	s_cmp_eq_u64 vcc, exec
	s_cselect_b64 s[42:43], -1, 0
	s_barrier
	s_waitcnt vmcnt(4)
	v_cndmask_b32_e64 v164, v164, 1.0, s[42:43]
	v_cmp_gt_f32_e32 vcc, 1.0, v164
	s_waitcnt vmcnt(3)
	ds_write_b128 v195, v[148:151] offset:16384
	s_waitcnt vmcnt(2)
	ds_write_b128 v208, v[152:155] offset:16384
	s_waitcnt vmcnt(1)
	ds_write_b128 v193, v[156:159] offset:49152
	s_waitcnt vmcnt(0)
	ds_write_b128 v194, v[160:163] offset:49152
	s_cbranch_vccz .LBB0_463
	s_and_saveexec_b64 s[20:21], s[40:41]
	ds_write_b32 v189, v164 offset:128
	s_or_b64 exec, exec, s[20:21]
	s_waitcnt lgkmcnt(0)
	v_add_u32_e32 v160, v188, v98
	ds_read_b128 v[148:151], v160 offset:224
	ds_read_b128 v[152:155], v160 offset:192
	ds_read_b128 v[156:159], v160 offset:160
	ds_read_b128 v[160:163], v160 offset:128
	s_waitcnt lgkmcnt(3)
	v_pk_mul_f32 v[14:15], v[14:15], v[148:149]
	s_waitcnt lgkmcnt(2)
	v_pk_mul_f32 v[10:11], v[10:11], v[152:153]
	s_waitcnt lgkmcnt(1)
	v_pk_mul_f32 v[6:7], v[6:7], v[156:157]
	v_pk_mul_f32 v[16:17], v[16:17], v[150:151]
	v_pk_mul_f32 v[12:13], v[12:13], v[154:155]
	v_pk_mul_f32 v[8:9], v[8:9], v[158:159]
	s_waitcnt lgkmcnt(0)
	v_pk_mul_f32 v[4:5], v[4:5], v[162:163]
	v_pk_mul_f32 v[2:3], v[2:3], v[160:161]
	v_pk_mul_f32 v[62:63], v[62:63], v[148:149]
	v_pk_mul_f32 v[58:59], v[58:59], v[152:153]
	v_pk_mul_f32 v[54:55], v[54:55], v[156:157]
	v_pk_mul_f32 v[64:65], v[64:65], v[150:151]
	v_pk_mul_f32 v[60:61], v[60:61], v[154:155]
	v_pk_mul_f32 v[56:57], v[56:57], v[158:159]
	v_pk_mul_f32 v[52:53], v[52:53], v[162:163]
	v_pk_mul_f32 v[50:51], v[50:51], v[160:161]
	v_pk_mul_f32 v[46:47], v[46:47], v[148:149]
	v_pk_mul_f32 v[42:43], v[42:43], v[152:153]
	v_pk_mul_f32 v[38:39], v[38:39], v[156:157]
	v_pk_mul_f32 v[48:49], v[48:49], v[150:151]
	v_pk_mul_f32 v[44:45], v[44:45], v[154:155]
	v_pk_mul_f32 v[40:41], v[40:41], v[158:159]
	v_pk_mul_f32 v[36:37], v[36:37], v[162:163]
	v_pk_mul_f32 v[34:35], v[34:35], v[160:161]
	v_pk_mul_f32 v[30:31], v[30:31], v[148:149]
	v_pk_mul_f32 v[26:27], v[26:27], v[152:153]
	v_pk_mul_f32 v[22:23], v[22:23], v[156:157]
	v_pk_mul_f32 v[32:33], v[32:33], v[150:151]
	v_pk_mul_f32 v[28:29], v[28:29], v[154:155]
	v_pk_mul_f32 v[24:25], v[24:25], v[158:159]
	v_pk_mul_f32 v[20:21], v[20:21], v[162:163]
	v_pk_mul_f32 v[18:19], v[18:19], v[160:161]
